# grid barriers: non-leader arrivers start an early L2 write-back before polling
# baseline (speedup 1.0000x reference)
; __device__ __forceinline__ unsigned xb_ld(unsigned* p)              { return __hip_atomic_load(p, __ATOMIC_RELAXED, __HIP_MEMORY_SCOPE_AGENT); }
; __device__ __forceinline__ unsigned xb_add(unsigned* p, unsigned v) { return __hip_atomic_fetch_add(p, v, __ATOMIC_RELAXED, __HIP_MEMORY_SCOPE_AGENT); }
; #define XB_SPIN(cond) do { unsigned _sp = 0; while (cond) { __builtin_amdgcn_s_sleep(1); if (++_sp > (1u << 24)) break; } } while (0)
; __device__ __forceinline__ void grid_barrier(unsigned* bar, volatile LAS unsigned* st, unsigned k) {
;     ...
;     const unsigned old = xb_add(&bar[XB_XSUB(x)], 1u);
;     if (old + 1u == (k + 1u) * nloc) {
;       __builtin_amdgcn_fence(__ATOMIC_RELEASE, "agent");
;       asm volatile("s_waitcnt vmcnt(0)" ::: "memory");
;       const unsigned og = xb_add(&bar[XB_TOP], 1u);
;       if (og + 1u == (k + 1u) * nx) xb_add(&bar[XB_TOPGEN], 1u);
;       else XB_SPIN(xb_ld(&bar[XB_TOPGEN]) == k);
;       __builtin_amdgcn_fence(__ATOMIC_ACQUIRE, "agent");
;       xb_add(&bar[XB_XGEN(x)], 1u);
;       asm volatile("s_waitcnt vmcnt(0)" ::: "memory");
;     } else {
;       XB_SPIN(xb_ld(&bar[XB_XGEN(x)]) == k);
;       __builtin_amdgcn_fence(__ATOMIC_ACQUIRE, "agent");
;       asm volatile("s_waitcnt vmcnt(0)" ::: "memory");
;     }
.LBB0_280:
	s_or_b64 exec, exec, s[10:11]
	s_waitcnt vmcnt(0)
	v_readfirstlane_b32 s8, v4
	s_nop 1
	v_add3_u32 v3, s8, v3, 1
	v_cmp_ne_u32_e32 vcc, v3, v2
	s_and_saveexec_b64 s[8:9], vcc
	s_xor_b64 s[8:9], exec, s[8:9]
	s_cbranch_execz .LBB0_295
	s_add_i32 s10, s3, 0x900
	s_mov_b32 s11, 0
	s_lshl_b64 s[10:11], s[10:11], 2
	s_add_u32 s10, s0, s10
	s_addc_u32 s11, s1, s11
	s_mov_b32 s18, 0x1000000
	buffer_wbl2 sc1
	v_mov_b32_e32 v1, 0
	s_branch .LBB0_284

; __device__ __forceinline__ unsigned xb_ld(unsigned* p)              { return __hip_atomic_load(p, __ATOMIC_RELAXED, __HIP_MEMORY_SCOPE_AGENT); }
; __device__ __forceinline__ unsigned xb_add(unsigned* p, unsigned v) { return __hip_atomic_fetch_add(p, v, __ATOMIC_RELAXED, __HIP_MEMORY_SCOPE_AGENT); }
; #define XB_SPIN(cond) do { unsigned _sp = 0; while (cond) { __builtin_amdgcn_s_sleep(1); if (++_sp > (1u << 24)) break; } } while (0)
; __device__ __forceinline__ void grid_barrier(unsigned* bar, volatile LAS unsigned* st, unsigned k) {
;     ...
;     const unsigned old = xb_add(&bar[XB_XSUB(x)], 1u);
;     if (old + 1u == (k + 1u) * nloc) {
;       __builtin_amdgcn_fence(__ATOMIC_RELEASE, "agent");
;       asm volatile("s_waitcnt vmcnt(0)" ::: "memory");
;       const unsigned og = xb_add(&bar[XB_TOP], 1u);
;       if (og + 1u == (k + 1u) * nx) xb_add(&bar[XB_TOPGEN], 1u);
;       else XB_SPIN(xb_ld(&bar[XB_TOPGEN]) == k);
;       __builtin_amdgcn_fence(__ATOMIC_ACQUIRE, "agent");
;       xb_add(&bar[XB_XGEN(x)], 1u);
;       asm volatile("s_waitcnt vmcnt(0)" ::: "memory");
;     } else {
;       XB_SPIN(xb_ld(&bar[XB_XGEN(x)]) == k);
;       __builtin_amdgcn_fence(__ATOMIC_ACQUIRE, "agent");
;       asm volatile("s_waitcnt vmcnt(0)" ::: "memory");
;     }
.LBB0_346:
	s_or_b64 exec, exec, s[8:9]
	s_waitcnt vmcnt(0)
	v_readfirstlane_b32 s6, v3
	v_mul_lo_u32 v1, v1, s0
	s_nop 0
	v_add3_u32 v2, s6, v2, 1
	v_cmp_ne_u32_e32 vcc, v2, v1
	s_and_saveexec_b64 s[6:7], vcc
	s_xor_b64 s[6:7], exec, s[6:7]
	s_cbranch_execz .LBB0_361
	s_add_i32 s8, s18, 0x900
	s_mov_b32 s9, 0
	s_lshl_b64 s[8:9], s[8:9], 2
	s_add_u32 s8, s1, s8
	s_addc_u32 s9, s3, s9
	s_mov_b32 s16, 0x1000000
	buffer_wbl2 sc1
	v_mov_b32_e32 v0, 0
	s_branch .LBB0_350

; __device__ __forceinline__ unsigned xb_ld(unsigned* p)              { return __hip_atomic_load(p, __ATOMIC_RELAXED, __HIP_MEMORY_SCOPE_AGENT); }
; __device__ __forceinline__ unsigned xb_add(unsigned* p, unsigned v) { return __hip_atomic_fetch_add(p, v, __ATOMIC_RELAXED, __HIP_MEMORY_SCOPE_AGENT); }
; #define XB_SPIN(cond) do { unsigned _sp = 0; while (cond) { __builtin_amdgcn_s_sleep(1); if (++_sp > (1u << 24)) break; } } while (0)
; __device__ __forceinline__ void grid_barrier(unsigned* bar, volatile LAS unsigned* st, unsigned k) {
;     ...
;     const unsigned old = xb_add(&bar[XB_XSUB(x)], 1u);
;     if (old + 1u == (k + 1u) * nloc) {
;       __builtin_amdgcn_fence(__ATOMIC_RELEASE, "agent");
;       asm volatile("s_waitcnt vmcnt(0)" ::: "memory");
;       const unsigned og = xb_add(&bar[XB_TOP], 1u);
;       if (og + 1u == (k + 1u) * nx) xb_add(&bar[XB_TOPGEN], 1u);
;       else XB_SPIN(xb_ld(&bar[XB_TOPGEN]) == k);
;       __builtin_amdgcn_fence(__ATOMIC_ACQUIRE, "agent");
;       xb_add(&bar[XB_XGEN(x)], 1u);
;       asm volatile("s_waitcnt vmcnt(0)" ::: "memory");
;     } else {
;       XB_SPIN(xb_ld(&bar[XB_XGEN(x)]) == k);
;       __builtin_amdgcn_fence(__ATOMIC_ACQUIRE, "agent");
;       asm volatile("s_waitcnt vmcnt(0)" ::: "memory");
;     }
.LBB0_429:
	s_or_b64 exec, exec, s[8:9]
	s_waitcnt vmcnt(0)
	v_readfirstlane_b32 s6, v3
	v_mul_lo_u32 v1, v1, s0
	s_nop 0
	v_add3_u32 v2, s6, v2, 1
	v_cmp_ne_u32_e32 vcc, v2, v1
	s_and_saveexec_b64 s[6:7], vcc
	s_xor_b64 s[6:7], exec, s[6:7]
	s_cbranch_execz .LBB0_444
	s_add_i32 s8, s16, 0x900
	s_mov_b32 s9, 0
	s_lshl_b64 s[8:9], s[8:9], 2
	s_add_u32 s8, s1, s8
	s_addc_u32 s9, s3, s9
	s_mov_b32 s12, 0x1000000
	buffer_wbl2 sc1
	v_mov_b32_e32 v0, 0
	s_branch .LBB0_433

; __device__ __forceinline__ unsigned xb_ld(unsigned* p)              { return __hip_atomic_load(p, __ATOMIC_RELAXED, __HIP_MEMORY_SCOPE_AGENT); }
; __device__ __forceinline__ unsigned xb_add(unsigned* p, unsigned v) { return __hip_atomic_fetch_add(p, v, __ATOMIC_RELAXED, __HIP_MEMORY_SCOPE_AGENT); }
; #define XB_SPIN(cond) do { unsigned _sp = 0; while (cond) { __builtin_amdgcn_s_sleep(1); if (++_sp > (1u << 24)) break; } } while (0)
; __device__ __forceinline__ void grid_barrier(unsigned* bar, volatile LAS unsigned* st, unsigned k) {
;     ...
;     const unsigned old = xb_add(&bar[XB_XSUB(x)], 1u);
;     if (old + 1u == (k + 1u) * nloc) {
;       __builtin_amdgcn_fence(__ATOMIC_RELEASE, "agent");
;       asm volatile("s_waitcnt vmcnt(0)" ::: "memory");
;       const unsigned og = xb_add(&bar[XB_TOP], 1u);
;       if (og + 1u == (k + 1u) * nx) xb_add(&bar[XB_TOPGEN], 1u);
;       else XB_SPIN(xb_ld(&bar[XB_TOPGEN]) == k);
;       __builtin_amdgcn_fence(__ATOMIC_ACQUIRE, "agent");
;       xb_add(&bar[XB_XGEN(x)], 1u);
;       asm volatile("s_waitcnt vmcnt(0)" ::: "memory");
;     } else {
;       XB_SPIN(xb_ld(&bar[XB_XGEN(x)]) == k);
;       __builtin_amdgcn_fence(__ATOMIC_ACQUIRE, "agent");
;       asm volatile("s_waitcnt vmcnt(0)" ::: "memory");
;     }
.LBB0_851:
	s_or_b64 exec, exec, s[8:9]
	s_waitcnt vmcnt(0)
	v_readfirstlane_b32 s6, v3
	v_mul_lo_u32 v1, v1, s0
	s_nop 0
	v_add3_u32 v2, s6, v2, 1
	v_cmp_ne_u32_e32 vcc, v2, v1
	s_and_saveexec_b64 s[6:7], vcc
	s_xor_b64 s[6:7], exec, s[6:7]
	s_cbranch_execz .LBB0_866
	s_add_i32 s8, s17, 0x900
	s_mov_b32 s9, 0
	s_lshl_b64 s[8:9], s[8:9], 2
	s_add_u32 s8, s1, s8
	s_addc_u32 s9, s16, s9
	s_mov_b32 s12, 0x1000000
	buffer_wbl2 sc1
	v_mov_b32_e32 v0, 0
	s_branch .LBB0_855

; __device__ __forceinline__ unsigned xb_ld(unsigned* p)              { return __hip_atomic_load(p, __ATOMIC_RELAXED, __HIP_MEMORY_SCOPE_AGENT); }
; __device__ __forceinline__ unsigned xb_add(unsigned* p, unsigned v) { return __hip_atomic_fetch_add(p, v, __ATOMIC_RELAXED, __HIP_MEMORY_SCOPE_AGENT); }
; #define XB_SPIN(cond) do { unsigned _sp = 0; while (cond) { __builtin_amdgcn_s_sleep(1); if (++_sp > (1u << 24)) break; } } while (0)
; __device__ __forceinline__ void grid_barrier(unsigned* bar, volatile LAS unsigned* st, unsigned k) {
;     ...
;     const unsigned old = xb_add(&bar[XB_XSUB(x)], 1u);
;     if (old + 1u == (k + 1u) * nloc) {
;       __builtin_amdgcn_fence(__ATOMIC_RELEASE, "agent");
;       asm volatile("s_waitcnt vmcnt(0)" ::: "memory");
;       const unsigned og = xb_add(&bar[XB_TOP], 1u);
;       if (og + 1u == (k + 1u) * nx) xb_add(&bar[XB_TOPGEN], 1u);
;       else XB_SPIN(xb_ld(&bar[XB_TOPGEN]) == k);
;       __builtin_amdgcn_fence(__ATOMIC_ACQUIRE, "agent");
;       xb_add(&bar[XB_XGEN(x)], 1u);
;       asm volatile("s_waitcnt vmcnt(0)" ::: "memory");
;     } else {
;       XB_SPIN(xb_ld(&bar[XB_XGEN(x)]) == k);
;       __builtin_amdgcn_fence(__ATOMIC_ACQUIRE, "agent");
;       asm volatile("s_waitcnt vmcnt(0)" ::: "memory");
;     }
.LBB0_1177:
	s_or_b64 exec, exec, s[8:9]
	s_waitcnt vmcnt(0)
	v_readfirstlane_b32 s6, v3
	v_mul_lo_u32 v1, v1, s0
	s_nop 0
	v_add3_u32 v2, s6, v2, 1
	v_cmp_ne_u32_e32 vcc, v2, v1
	s_and_saveexec_b64 s[6:7], vcc
	s_xor_b64 s[6:7], exec, s[6:7]
	s_cbranch_execz .LBB0_1192
	s_add_i32 s8, s15, 0x900
	s_mov_b32 s9, 0
	s_lshl_b64 s[8:9], s[8:9], 2
	s_add_u32 s8, s1, s8
	s_addc_u32 s9, s14, s9
	s_mov_b32 s12, 0x1000000
	buffer_wbl2 sc1
	v_mov_b32_e32 v0, 0
	s_branch .LBB0_1181

; __device__ __forceinline__ unsigned xb_ld(unsigned* p)              { return __hip_atomic_load(p, __ATOMIC_RELAXED, __HIP_MEMORY_SCOPE_AGENT); }
; __device__ __forceinline__ unsigned xb_add(unsigned* p, unsigned v) { return __hip_atomic_fetch_add(p, v, __ATOMIC_RELAXED, __HIP_MEMORY_SCOPE_AGENT); }
; #define XB_SPIN(cond) do { unsigned _sp = 0; while (cond) { __builtin_amdgcn_s_sleep(1); if (++_sp > (1u << 24)) break; } } while (0)
; __device__ __forceinline__ void grid_barrier(unsigned* bar, volatile LAS unsigned* st, unsigned k) {
;     ...
;     const unsigned old = xb_add(&bar[XB_XSUB(x)], 1u);
;     if (old + 1u == (k + 1u) * nloc) {
;       __builtin_amdgcn_fence(__ATOMIC_RELEASE, "agent");
;       asm volatile("s_waitcnt vmcnt(0)" ::: "memory");
;       const unsigned og = xb_add(&bar[XB_TOP], 1u);
;       if (og + 1u == (k + 1u) * nx) xb_add(&bar[XB_TOPGEN], 1u);
;       else XB_SPIN(xb_ld(&bar[XB_TOPGEN]) == k);
;       __builtin_amdgcn_fence(__ATOMIC_ACQUIRE, "agent");
;       xb_add(&bar[XB_XGEN(x)], 1u);
;       asm volatile("s_waitcnt vmcnt(0)" ::: "memory");
;     } else {
;       XB_SPIN(xb_ld(&bar[XB_XGEN(x)]) == k);
;       __builtin_amdgcn_fence(__ATOMIC_ACQUIRE, "agent");
;       asm volatile("s_waitcnt vmcnt(0)" ::: "memory");
;     }
.LBB0_1366:
	s_or_b64 exec, exec, s[8:9]
	s_waitcnt vmcnt(0)
	v_readfirstlane_b32 s6, v3
	v_mul_lo_u32 v1, v1, s0
	s_nop 0
	v_add3_u32 v2, s6, v2, 1
	v_cmp_ne_u32_e32 vcc, v2, v1
	s_and_saveexec_b64 s[6:7], vcc
	s_xor_b64 s[6:7], exec, s[6:7]
	s_cbranch_execz .LBB0_1381
	s_add_i32 s8, s14, 0x900
	s_mov_b32 s9, 0
	s_lshl_b64 s[8:9], s[8:9], 2
	s_add_u32 s8, s1, s8
	s_addc_u32 s9, s3, s9
	s_mov_b32 s12, 0x1000000
	buffer_wbl2 sc1
	v_mov_b32_e32 v0, 0
	s_branch .LBB0_1370

; __device__ __forceinline__ unsigned xb_ld(unsigned* p)              { return __hip_atomic_load(p, __ATOMIC_RELAXED, __HIP_MEMORY_SCOPE_AGENT); }
; __device__ __forceinline__ unsigned xb_add(unsigned* p, unsigned v) { return __hip_atomic_fetch_add(p, v, __ATOMIC_RELAXED, __HIP_MEMORY_SCOPE_AGENT); }
; #define XB_SPIN(cond) do { unsigned _sp = 0; while (cond) { __builtin_amdgcn_s_sleep(1); if (++_sp > (1u << 24)) break; } } while (0)
; __device__ __forceinline__ void grid_barrier(unsigned* bar, volatile LAS unsigned* st, unsigned k) {
;     ...
;     const unsigned old = xb_add(&bar[XB_XSUB(x)], 1u);
;     if (old + 1u == (k + 1u) * nloc) {
;       __builtin_amdgcn_fence(__ATOMIC_RELEASE, "agent");
;       asm volatile("s_waitcnt vmcnt(0)" ::: "memory");
;       const unsigned og = xb_add(&bar[XB_TOP], 1u);
;       if (og + 1u == (k + 1u) * nx) xb_add(&bar[XB_TOPGEN], 1u);
;       else XB_SPIN(xb_ld(&bar[XB_TOPGEN]) == k);
;       __builtin_amdgcn_fence(__ATOMIC_ACQUIRE, "agent");
;       xb_add(&bar[XB_XGEN(x)], 1u);
;       asm volatile("s_waitcnt vmcnt(0)" ::: "memory");
;     } else {
;       XB_SPIN(xb_ld(&bar[XB_XGEN(x)]) == k);
;       __builtin_amdgcn_fence(__ATOMIC_ACQUIRE, "agent");
;       asm volatile("s_waitcnt vmcnt(0)" ::: "memory");
;     }
.LBB0_1677:
	s_or_b64 exec, exec, s[0:1]
	s_waitcnt vmcnt(0)
	v_readfirstlane_b32 s0, v3
	v_mul_lo_u32 v1, v1, s3
	s_nop 0
	v_add3_u32 v2, s0, v2, 1
	v_cmp_ne_u32_e32 vcc, v2, v1
	s_and_saveexec_b64 s[0:1], vcc
	s_xor_b64 s[6:7], exec, s[0:1]
	s_cbranch_execz .LBB0_1692
	s_add_i32 s0, s14, 0x900
	s_mov_b32 s1, 0
	s_lshl_b64 s[0:1], s[0:1], 2
	s_add_u32 s8, s12, s0
	s_addc_u32 s9, s13, s1
	s_mov_b32 s0, 0x1000000
	buffer_wbl2 sc1
	v_mov_b32_e32 v0, 0
	s_branch .LBB0_1681

; __device__ __forceinline__ unsigned xb_ld(unsigned* p)              { return __hip_atomic_load(p, __ATOMIC_RELAXED, __HIP_MEMORY_SCOPE_AGENT); }
; __device__ __forceinline__ unsigned xb_add(unsigned* p, unsigned v) { return __hip_atomic_fetch_add(p, v, __ATOMIC_RELAXED, __HIP_MEMORY_SCOPE_AGENT); }
; #define XB_SPIN(cond) do { unsigned _sp = 0; while (cond) { __builtin_amdgcn_s_sleep(1); if (++_sp > (1u << 24)) break; } } while (0)
; __device__ __forceinline__ void grid_barrier(unsigned* bar, volatile LAS unsigned* st, unsigned k) {
;     ...
;     const unsigned old = xb_add(&bar[XB_XSUB(x)], 1u);
;     if (old + 1u == (k + 1u) * nloc) {
;       __builtin_amdgcn_fence(__ATOMIC_RELEASE, "agent");
;       asm volatile("s_waitcnt vmcnt(0)" ::: "memory");
;       const unsigned og = xb_add(&bar[XB_TOP], 1u);
;       if (og + 1u == (k + 1u) * nx) xb_add(&bar[XB_TOPGEN], 1u);
;       else XB_SPIN(xb_ld(&bar[XB_TOPGEN]) == k);
;       __builtin_amdgcn_fence(__ATOMIC_ACQUIRE, "agent");
;       xb_add(&bar[XB_XGEN(x)], 1u);
;       asm volatile("s_waitcnt vmcnt(0)" ::: "memory");
;     } else {
;       XB_SPIN(xb_ld(&bar[XB_XGEN(x)]) == k);
;       __builtin_amdgcn_fence(__ATOMIC_ACQUIRE, "agent");
;       asm volatile("s_waitcnt vmcnt(0)" ::: "memory");
;     }
.LBB0_1725:
	s_or_b64 exec, exec, s[4:5]
	s_waitcnt vmcnt(0)
	v_readfirstlane_b32 s2, v3
	s_add_i32 s8, s33, 1
	v_mul_lo_u32 v1, v1, s8
	v_add3_u32 v2, s2, v2, 1
	v_cmp_ne_u32_e32 vcc, v2, v1
	s_and_saveexec_b64 s[2:3], vcc
	s_xor_b64 s[2:3], exec, s[2:3]
	s_cbranch_execz .LBB0_1740
	s_add_i32 s4, s12, 0x900
	s_mov_b32 s5, 0
	s_lshl_b64 s[4:5], s[4:5], 2
	s_add_u32 s4, s10, s4
	s_addc_u32 s5, s11, s5
	s_mov_b32 s9, 0x1000000
	buffer_wbl2 sc1
	v_mov_b32_e32 v0, 0
	s_branch .LBB0_1729
